# v19 + NSA staging via per-item SGPR base + v_perm_b32 interleave (32 instead of 53 instructions per tile), LIST pointer in a VGPR, v_mov_b64 accumulator-init fill
# speedup vs baseline: 1.0127x; 1.0012x over previous
; DI f32x16 mma32(bf16x8 a, bf16x8 b, f32x16 c) { return __builtin_amdgcn_mfma_f32_32x32x16_bf16(a, b, c, 0, 0, 0); }
; DI bf16x8 packp(const f32x16& x, const int h8) { v4u p; p.x = pk2(x[h8 + 0], x[h8 + 1]); p.y = pk2(x[h8 + 2], x[h8 + 3]); p.z = pk2(x[h8 + 4], x[h8 + 5]); p.w = pk2(x[h8 + 6], x[h8 + 7]); return __builtin_bit_cast(bf16x8, p); }
; DI void nsa_item(KA a, LAS unsigned char* lds, const int it) {
;     ...
;         f32x16 ot[2] = {ZERO16, ZERO16};
; #pragma unroll
;         for (int sp = 0; sp < 8; ++sp) { const bf16x8 pf = packp(st[sp >> 1], 8 * (sp & 1));
; #pragma unroll
;             for (int dh = 0; dh < 2; ++dh) ot[dh] = mma32(vfrag(VT, 32 * dh + r, sp, hf), pf, ot[dh]); }
;         of[0] = ot[0] * g0; of[1] = ot[1] * g0;
.LBB0_794:
	v_add_f32_e32 v33, 1.0, v33
	v_rcp_f32_e32 v34, v33
	s_andn2_b64 vcc, exec, s[0:1]
	v_readlane_b32 s90, v254, 47
	v_pk_mul_f32 v[124:125], v[34:35], v[30:31] op_sel_hi:[0,1]
	v_pk_mul_f32 v[120:121], v[34:35], v[28:29] op_sel_hi:[0,1]
	v_pk_mul_f32 v[116:117], v[34:35], v[26:27] op_sel_hi:[0,1]
	v_pk_mul_f32 v[112:113], v[34:35], v[24:25] op_sel_hi:[0,1]
	v_pk_mul_f32 v[108:109], v[34:35], v[22:23] op_sel_hi:[0,1]
	v_pk_mul_f32 v[104:105], v[34:35], v[20:21] op_sel_hi:[0,1]
	v_pk_mul_f32 v[100:101], v[34:35], v[18:19] op_sel_hi:[0,1]
	v_pk_mul_f32 v[96:97], v[34:35], v[16:17] op_sel_hi:[0,1]
	v_pk_mul_f32 v[122:123], v[34:35], v[14:15] op_sel_hi:[0,1]
	v_pk_mul_f32 v[118:119], v[34:35], v[12:13] op_sel_hi:[0,1]
	v_pk_mul_f32 v[114:115], v[34:35], v[10:11] op_sel_hi:[0,1]
	v_pk_mul_f32 v[110:111], v[34:35], v[8:9] op_sel_hi:[0,1]
	v_pk_mul_f32 v[106:107], v[34:35], v[6:7] op_sel_hi:[0,1]
	v_pk_mul_f32 v[102:103], v[34:35], v[4:5] op_sel_hi:[0,1]
	v_pk_mul_f32 v[98:99], v[34:35], v[2:3] op_sel_hi:[0,1]
	v_pk_mul_f32 v[94:95], v[34:35], v[0:1] op_sel_hi:[0,1]
	v_mov_b32_e32 v31, 0
	s_cbranch_vccnz .LBB0_811
	v_cmp_gt_u32_e64 s[0:1], v92, v135
	v_or_b32_e32 v0, 2, v92
	s_sub_i32 s85, 23, s40
	v_writelane_b32 v254, s0, 49
	s_mov_b32 s87, 0
	s_mov_b32 s88, 0
	v_writelane_b32 v254, s1, 50
	v_cmp_le_u32_e64 s[0:1], v92, v135
	v_mov_b32_e32 v137, 0
	v_mov_b32_e32 v16, 0
	v_writelane_b32 v254, s0, 51
	s_nop 1
	v_writelane_b32 v254, s1, 52
	v_cmp_ge_u32_e64 s[0:1], v92, v135
	s_nop 1
	v_writelane_b32 v254, s0, 53
	s_nop 1
	v_writelane_b32 v254, s1, 54
	v_cmp_lt_u32_e64 s[0:1], v92, v135
	s_nop 1
	v_writelane_b32 v254, s0, 55
	s_nop 1
	v_writelane_b32 v254, s1, 56
	v_cmp_gt_u32_e64 s[0:1], v0, v135
	s_nop 1
	v_writelane_b32 v254, s0, 57
	s_nop 1
	v_writelane_b32 v254, s1, 58
	v_cmp_le_u32_e64 s[0:1], v0, v135
	v_or_b32_e32 v0, 3, v92
	s_nop 0
	v_writelane_b32 v254, s0, 59
	s_nop 1
	v_writelane_b32 v254, s1, 60
	v_cmp_gt_u32_e64 s[0:1], v0, v135
	s_nop 1
	v_writelane_b32 v254, s0, 61
	s_nop 1
	v_writelane_b32 v254, s1, 62
	v_cmp_le_u32_e64 s[0:1], v0, v135
	v_or_b32_e32 v0, 8, v92
	s_nop 0
	v_writelane_b32 v254, s0, 63
	s_nop 0
	v_readlane_b32 s86, v254, 13
	v_writelane_b32 v245, s1, 0
	v_cmp_gt_u32_e64 s[0:1], v0, v135
	s_nop 1
	v_writelane_b32 v245, s0, 1
	s_nop 1
	v_writelane_b32 v245, s1, 2
	v_cmp_le_u32_e64 s[0:1], v0, v135
	v_or_b32_e32 v0, 9, v92
	s_nop 0
	v_writelane_b32 v245, s0, 3
	s_nop 1
	v_writelane_b32 v245, s1, 4
	v_cmp_gt_u32_e64 s[0:1], v0, v135
	s_nop 1
	v_writelane_b32 v245, s0, 5
	s_nop 1
	v_writelane_b32 v245, s1, 6
	v_cmp_le_u32_e64 s[0:1], v0, v135
	v_or_b32_e32 v0, 10, v92
	s_nop 0
	v_writelane_b32 v245, s0, 7
	s_nop 1
	v_writelane_b32 v245, s1, 8
	v_cmp_gt_u32_e64 s[0:1], v0, v135
	s_nop 1
	v_writelane_b32 v245, s0, 9
	s_nop 1
	v_writelane_b32 v245, s1, 10
	v_cmp_le_u32_e64 s[0:1], v0, v135
	v_or_b32_e32 v0, 11, v92
	s_nop 0
	v_writelane_b32 v245, s0, 11
	s_nop 1
	v_writelane_b32 v245, s1, 12
	v_cmp_gt_u32_e64 s[0:1], v0, v135
	s_nop 1
	v_writelane_b32 v245, s0, 13
	s_nop 1
	v_writelane_b32 v245, s1, 14
	v_cmp_le_u32_e64 s[0:1], v0, v135
	v_or_b32_e32 v0, 16, v92
	s_nop 0
	v_writelane_b32 v245, s0, 15
	s_nop 1
	v_writelane_b32 v245, s1, 16
	v_cmp_gt_u32_e64 s[0:1], v0, v135
	s_nop 1
	v_writelane_b32 v245, s0, 17
	s_nop 1
	v_writelane_b32 v245, s1, 18
	v_cmp_le_u32_e64 s[0:1], v0, v135
	v_or_b32_e32 v0, 17, v92
	s_nop 0
	v_writelane_b32 v245, s0, 19
	s_nop 1
	v_writelane_b32 v245, s1, 20
	v_cmp_gt_u32_e64 s[0:1], v0, v135
	s_nop 1
	v_writelane_b32 v245, s0, 21
	s_nop 1
	v_writelane_b32 v245, s1, 22
	v_cmp_le_u32_e64 s[0:1], v0, v135
	v_or_b32_e32 v0, 18, v92
	s_nop 0
	v_writelane_b32 v245, s0, 23
	s_nop 1
	v_writelane_b32 v245, s1, 24
	v_cmp_gt_u32_e64 s[0:1], v0, v135
	s_nop 1
	v_writelane_b32 v245, s0, 25
	s_nop 1
	v_writelane_b32 v245, s1, 26
	v_cmp_le_u32_e64 s[0:1], v0, v135
	v_or_b32_e32 v0, 19, v92
	s_nop 0
	v_writelane_b32 v245, s0, 27
	s_nop 1
	v_writelane_b32 v245, s1, 28
	v_cmp_gt_u32_e64 s[0:1], v0, v135
	s_nop 1
	v_writelane_b32 v245, s0, 29
	s_nop 1
	v_writelane_b32 v245, s1, 30
	v_cmp_le_u32_e64 s[0:1], v0, v135
	v_or_b32_e32 v0, 24, v92
	s_nop 0
	v_writelane_b32 v245, s0, 31
	s_nop 1
	v_writelane_b32 v245, s1, 32
	v_cmp_gt_u32_e64 s[0:1], v0, v135
	s_nop 1
; #define LAS __attribute__((address_space(3)))
; #define NSA_STORE(Kb, Vb) do { *(LAS v4u*)((Kb) + skey * PA + 8 * sch) = kreg; LAS unsigned* d0_ = (LAS unsigned*)((Vb) + (4 * sdg) * PV + vpos(2 * skp)); \
;         d0_[0] = (vr0.x & 0xffffu) | (vr1.x << 16); d0_[PV / 2] = (vr0.x >> 16) | (vr1.x & 0xffff0000u); d0_[PV] = (vr0.y & 0xffffu) | (vr1.y << 16); d0_[3 * PV / 2] = (vr0.y >> 16) | (vr1.y & 0xffff0000u); } while (0)
; DI void nsa_item(KA a, LAS unsigned char* lds, const int it) {
;     ...
;     const unsigned mysel = SELM[tql]; const int n = *NLIST;
;     LAS bf16* Kt1 = (LAS bf16*)(lds + NSA_KT1); LAS bf16* VT1 = (LAS bf16*)(lds + NSA_VT1);
;     NSA_STORE(Kt, VT);
;     NSA_LOAD(LIST[1]);
;     __syncthreads();
;     float m_ref = 0.f, l_run = 0.f; f32x16 ot[2] = {ZERO16, ZERO16}; int curtype = 0;
	v_writelane_b32 v245, s0, 33
	s_nop 1
	v_writelane_b32 v245, s1, 34
	v_cmp_le_u32_e64 s[0:1], v0, v135
	v_or_b32_e32 v0, 25, v92
	v_cmp_gt_u32_e64 s[92:93], v0, v135
	v_cmp_le_u32_e64 s[94:95], v0, v135
	v_or_b32_e32 v0, 26, v92
	v_cmp_gt_u32_e64 s[96:97], v0, v135
	v_cmp_le_u32_e64 s[6:7], v0, v135
	v_or_b32_e32 v0, 27, v92
	v_cmp_gt_u32_e64 s[8:9], v0, v135
	v_cmp_le_u32_e64 s[10:11], v0, v135
	v_or_b32_e32 v0, 32, v92
	v_cmp_gt_u32_e64 s[12:13], v0, v135
	v_cmp_le_u32_e64 s[14:15], v0, v135
	v_or_b32_e32 v0, 33, v92
	v_cmp_gt_u32_e64 s[16:17], v0, v135
	v_cmp_le_u32_e64 s[18:19], v0, v135
	v_or_b32_e32 v0, 34, v92
	v_cmp_gt_u32_e64 s[20:21], v0, v135
	v_cmp_le_u32_e64 s[22:23], v0, v135
	v_or_b32_e32 v0, 35, v92
	v_cmp_gt_u32_e64 s[24:25], v0, v135
	v_cmp_le_u32_e64 s[26:27], v0, v135
	v_or_b32_e32 v0, 40, v92
	v_cmp_gt_u32_e64 s[28:29], v0, v135
	v_cmp_le_u32_e64 s[30:31], v0, v135
	v_or_b32_e32 v0, 41, v92
	v_cmp_gt_u32_e64 s[34:35], v0, v135
	v_cmp_le_u32_e64 s[36:37], v0, v135
	v_or_b32_e32 v0, 42, v92
	v_cmp_gt_u32_e64 s[38:39], v0, v135
	v_cmp_le_u32_e64 s[4:5], v0, v135
	v_or_b32_e32 v0, 43, v92
	v_writelane_b32 v245, s0, 35
	v_cmp_gt_u32_e64 s[40:41], v0, v135
	v_cmp_le_u32_e64 s[2:3], v0, v135
	v_or_b32_e32 v0, 48, v92
	v_writelane_b32 v245, s1, 36
	v_cmp_gt_u32_e64 s[0:1], v0, v135
	v_cmp_le_u32_e64 s[42:43], v0, v135
	v_or_b32_e32 v0, 49, v92
	v_cmp_gt_u32_e64 s[44:45], v0, v135
	v_cmp_le_u32_e64 s[46:47], v0, v135
	v_or_b32_e32 v0, 50, v92
	v_cmp_gt_u32_e64 s[48:49], v0, v135
	v_cmp_le_u32_e64 s[50:51], v0, v135
	v_or_b32_e32 v0, 51, v92
	v_cmp_gt_u32_e64 s[52:53], v0, v135
	v_cmp_le_u32_e64 s[54:55], v0, v135
	v_or_b32_e32 v0, 56, v92
	v_cmp_gt_u32_e64 s[56:57], v0, v135
	v_cmp_le_u32_e64 s[58:59], v0, v135
	v_or_b32_e32 v0, 57, v92
	v_cmp_gt_u32_e64 s[60:61], v0, v135
	v_cmp_le_u32_e64 s[62:63], v0, v135
	v_or_b32_e32 v0, 58, v92
	v_cmp_gt_u32_e64 s[64:65], v0, v135
	v_cmp_le_u32_e64 s[66:67], v0, v135
	v_or_b32_e32 v0, 59, v92
	v_cmp_gt_u32_e64 s[68:69], v0, v135
	v_cmp_le_u32_e64 s[70:71], v0, v135
	v_mov_b32_e32 v135, 0
	v_mov_b32_e32 v0, 0
	v_mov_b32_e32 v1, v135
	v_mov_b32_e32 v2, v135
	v_mov_b32_e32 v3, v135
	v_mov_b32_e32 v4, v135
	v_mov_b32_e32 v5, v135
	v_mov_b32_e32 v6, v135
	v_mov_b32_e32 v7, v135
	v_mov_b32_e32 v8, v135
	v_mov_b32_e32 v9, v135
	v_mov_b32_e32 v10, v135
	v_mov_b32_e32 v11, v135
	v_mov_b32_e32 v12, v135
	v_mov_b32_e32 v13, v135
	v_mov_b32_e32 v14, v135
	v_mov_b32_e32 v15, v135
	v_mov_b32_e32 v17, v135
	v_mov_b32_e32 v18, v135
	v_mov_b32_e32 v19, v135
	v_mov_b32_e32 v20, v135
	v_mov_b32_e32 v21, v135
	v_mov_b32_e32 v22, v135
	v_mov_b32_e32 v23, v135
	v_mov_b32_e32 v24, v135
	v_mov_b32_e32 v25, v135
	v_mov_b32_e32 v26, v135
	v_mov_b32_e32 v27, v135
	v_mov_b32_e32 v28, v135
	v_mov_b32_e32 v29, v135
	v_mov_b32_e32 v30, v135
	v_mov_b32_e32 v31, v135
	s_movk_i32 s74, 0x1c00
	v_mad_u32_u24 v190, v132, s74, v192
	v_mad_u32_u24 v251, v133, s74, v88
	v_add_u32_e32 v251, 0x100, v251
	v_add_u32_e32 v241, 0x1c00, v251
	v_readlane_b32 s74, v254, 48
	v_readlane_b32 s98, v254, 39
	v_readlane_b32 s99, v254, 40
	s_mov_b32 s100, 0x5040100
	s_mul_i32 s74, s74, 0x1c00
	s_lshl_b32 s75, s33, 1
	s_add_u32 s74, s74, s75
	s_add_u32 s98, s98, s74
	s_addc_u32 s99, s99, 0
	s_mov_b32 s101, 0x7060302
	v_and_b32_e32 v242, 31, v238
	v_lshrrev_b32_e32 v243, 5, v238
	v_lshlrev_b32_e32 v243, 2, v243
	v_sub_u32_e32 v242, v242, v243
	v_bfe_u32 v243, v232, 6, 1
	v_lshl_add_u32 v242, v243, 5, v242
	v_add3_u32 v231, 0, v90, v130
	s_movk_i32 s74, 0x4800
	v_add3_u32 v230, s74, v90, v131
	ds_read_b128 v[170:173], v231 offset:64
	ds_read_b128 v[178:181], v231 offset:4608
	ds_read_b128 v[182:185], v231 offset:4640
	ds_read_b128 v[186:189], v231 offset:4672
	ds_read_b128 v[206:209], v231 offset:4704
	ds_read_b128 v[174:177], v231 offset:96
	s_add_i32 s74, s86, -8
	v_mov_b32_e32 v244, s74
	ds_read_b32 v191, v244
	ds_read_b32 v250, v244 offset:8
	ds_read_b128 v[210:213], v230
	ds_read_b128 v[218:221], v230 offset:8704
	ds_read_b128 v[222:225], v230 offset:8736
	ds_read_b128 v[214:217], v230 offset:32
	ds_read_b128 v[226:229], v230 offset:64
	ds_read_b128 v[152:155], v230 offset:8768
	ds_read_b128 v[246:249], v230 offset:96
	ds_read_b128 v[144:147], v231
	ds_read_b128 v[148:151], v231 offset:32

; #define LAS __attribute__((address_space(3)))
; DI f32x16 mma32(bf16x8 a, bf16x8 b, f32x16 c) { return __builtin_amdgcn_mfma_f32_32x32x16_bf16(a, b, c, 0, 0, 0); }
; DI int crow(int i, int hf) { return (i & 3) + 8 * (i >> 2) + 4 * hf; }
; DI void nsa_item(KA a, LAS unsigned char* lds, const int it) {
;     ...
;         const float init = rowoff ? -INFINITY : -m_ref;
;         f32x16 st[2];
; #pragma unroll
;         for (int i2 = 0; i2 < 16; ++i2) { st[0][i2] = init; st[1][i2] = init; }
; #pragma unroll
;         for (int kt = 0; kt < 2; ++kt)
; #pragma unroll
;             for (int s = 0; s < 4; ++s) { const bf16x8 af = *(const LAS bf16x8*)(Kc + (32 * kt + r) * PA + 16 * s + 8 * hf); st[kt] = mma32(af, bq[s], st[kt]); }
;         if (mode != 0) {
; #pragma unroll
;             for (int kt = 0; kt < 2; ++kt)
; #pragma unroll
;                 for (int i2 = 0; i2 < 16; ++i2) { const int kl = 32 * kt + crow(i2, hf); const bool bad = rowoff || (mode == 1 && kl > tql) || (mode == 2 && kl <= tql); st[kt][i2] = bad ? -INFINITY : st[kt][i2]; }
.LBB0_798:
	s_and_b32 s83, s78, 0xff
	s_cmpk_lt_u32 s78, 0x100
	s_cselect_b64 s[80:81], -1, 0
	s_lshl_b32 s78, 1, s78
	v_and_b32_e32 v32, s78, v141
	v_cmp_eq_u32_e32 vcc, 0, v32
	s_and_b64 s[78:79], s[80:81], vcc
	v_cndmask_b32_e64 v32, -v137, v240, s[78:79]
	v_mov_b32_e32 v33, v32
	v_mov_b64_e32 v[34:35], v[32:33]
	v_mov_b64_e32 v[36:37], v[32:33]
	v_mov_b64_e32 v[38:39], v[32:33]
	v_mov_b64_e32 v[40:41], v[32:33]
	v_mov_b64_e32 v[42:43], v[32:33]
	v_mov_b64_e32 v[44:45], v[32:33]
	v_mov_b64_e32 v[46:47], v[32:33]
	s_cmp_eq_u32 s83, s90
	s_cselect_b64 s[80:81], -1, 0
	s_nop 0
	v_mfma_f32_32x32x16_bf16 v[48:63], v[170:173], v[68:71], v[32:47]
	s_cmp_eq_u32 s83, s85
	s_cselect_b64 vcc, -1, 0
	s_cmp_eq_u32 s82, 1
	s_cselect_b64 s[82:83], -1, 0
	s_and_b64 s[82:83], s[82:83], vcc
	s_or_b64 vcc, s[80:81], s[82:83]
	s_andn2_b64 vcc, exec, vcc
	v_mfma_f32_32x32x16_bf16 v[32:47], v[178:181], v[72:75], v[32:47]
	v_mfma_f32_32x32x16_bf16 v[32:47], v[182:185], v[64:67], v[32:47]
	v_mfma_f32_32x32x16_bf16 v[32:47], v[186:189], v[68:71], v[32:47]
	v_mfma_f32_32x32x16_bf16 v[32:47], v[206:209], v[76:79], v[32:47]
	v_mfma_f32_32x32x16_bf16 v[48:63], v[174:177], v[76:79], v[48:63]
	s_waitcnt lgkmcnt(1)
	v_mfma_f32_32x32x16_bf16 v[48:63], v[144:147], v[72:75], v[48:63]
	s_waitcnt lgkmcnt(0)
	v_mfma_f32_32x32x16_bf16 v[48:63], v[148:151], v[64:67], v[48:63]
	ds_read_b128 v[148:151], v230 offset:8800
	s_cbranch_vccnz .LBB0_800
	s_and_b64 vcc, exec, s[80:81]
	s_nop 0
	s_cbranch_vccz .Lnsa_m2
	v_cmp_gt_i32_e64 s[74:75], 32, v242
	v_cmp_gt_i32_e64 s[76:77], 33, v242
	v_cmp_gt_i32_e64 s[78:79], 34, v242
	v_cndmask_b32_e64 v32, v32, v240, s[74:75]
	v_cmp_gt_i32_e64 s[74:75], 35, v242
	v_cndmask_b32_e64 v33, v33, v240, s[76:77]
	v_cmp_gt_i32_e64 s[76:77], 40, v242
	v_cndmask_b32_e64 v34, v34, v240, s[78:79]
	v_cmp_gt_i32_e64 s[78:79], 41, v242
	v_cndmask_b32_e64 v35, v35, v240, s[74:75]
	v_cmp_gt_i32_e64 s[74:75], 42, v242
	v_cndmask_b32_e64 v36, v36, v240, s[76:77]
	v_cmp_gt_i32_e64 s[76:77], 43, v242
	v_cndmask_b32_e64 v37, v37, v240, s[78:79]
	v_cmp_gt_i32_e64 s[78:79], 48, v242
	v_cndmask_b32_e64 v38, v38, v240, s[74:75]
	v_cmp_gt_i32_e64 s[74:75], 49, v242
	v_cndmask_b32_e64 v39, v39, v240, s[76:77]
	v_cmp_gt_i32_e64 s[76:77], 50, v242
	v_cndmask_b32_e64 v40, v40, v240, s[78:79]
	v_cmp_gt_i32_e64 s[78:79], 51, v242
	v_cndmask_b32_e64 v41, v41, v240, s[74:75]
	v_cmp_gt_i32_e64 s[74:75], 56, v242
	v_cndmask_b32_e64 v42, v42, v240, s[76:77]
	v_cmp_gt_i32_e64 s[76:77], 57, v242
	v_cndmask_b32_e64 v43, v43, v240, s[78:79]
	v_cmp_gt_i32_e64 s[78:79], 58, v242
	v_cndmask_b32_e64 v44, v44, v240, s[74:75]
	v_cmp_gt_i32_e64 s[74:75], 59, v242
	v_cndmask_b32_e64 v45, v45, v240, s[76:77]
	v_cmp_gt_i32_e64 s[76:77], 0, v242
	v_cndmask_b32_e64 v46, v46, v240, s[78:79]
	v_cmp_gt_i32_e64 s[78:79], 1, v242
	v_cndmask_b32_e64 v47, v47, v240, s[74:75]
	v_cmp_gt_i32_e64 s[74:75], 2, v242
	v_cndmask_b32_e64 v48, v48, v240, s[76:77]
	v_cmp_gt_i32_e64 s[76:77], 3, v242
	v_cndmask_b32_e64 v49, v49, v240, s[78:79]
	v_cmp_gt_i32_e64 s[78:79], 8, v242
	v_cndmask_b32_e64 v50, v50, v240, s[74:75]
	v_cmp_gt_i32_e64 s[74:75], 9, v242
	v_cndmask_b32_e64 v51, v51, v240, s[76:77]
	v_cmp_gt_i32_e64 s[76:77], 10, v242
	v_cndmask_b32_e64 v52, v52, v240, s[78:79]
	v_cmp_gt_i32_e64 s[78:79], 11, v242
	v_cndmask_b32_e64 v53, v53, v240, s[74:75]
	v_cmp_gt_i32_e64 s[74:75], 16, v242
	v_cndmask_b32_e64 v54, v54, v240, s[76:77]
	v_cmp_gt_i32_e64 s[76:77], 17, v242
	v_cndmask_b32_e64 v55, v55, v240, s[78:79]
	v_cmp_gt_i32_e64 s[78:79], 18, v242
	v_cndmask_b32_e64 v56, v56, v240, s[74:75]
	v_cmp_gt_i32_e64 s[74:75], 19, v242
	v_cndmask_b32_e64 v57, v57, v240, s[76:77]
	v_cmp_gt_i32_e64 s[76:77], 24, v242
	v_cndmask_b32_e64 v58, v58, v240, s[78:79]
	v_cmp_gt_i32_e64 s[78:79], 25, v242
	v_cndmask_b32_e64 v59, v59, v240, s[74:75]
	v_cmp_gt_i32_e64 s[74:75], 26, v242
	v_cndmask_b32_e64 v60, v60, v240, s[76:77]
	v_cmp_gt_i32_e64 s[76:77], 27, v242
	s_nop 0
	v_cndmask_b32_e64 v61, v61, v240, s[78:79]
	v_cndmask_b32_e64 v62, v62, v240, s[74:75]
	v_cndmask_b32_e64 v63, v63, v240, s[76:77]
	s_branch .LBB0_800

; #define NSA_STORE(Kb, Vb) do { *(LAS v4u*)((Kb) + skey * PA + 8 * sch) = kreg; LAS unsigned* d0_ = (LAS unsigned*)((Vb) + (4 * sdg) * PV + vpos(2 * skp)); \
;         d0_[0] = (vr0.x & 0xffffu) | (vr1.x << 16); d0_[PV / 2] = (vr0.x >> 16) | (vr1.x & 0xffff0000u); d0_[PV] = (vr0.y & 0xffffu) | (vr1.y << 16); d0_[3 * PV / 2] = (vr0.y >> 16) | (vr1.y & 0xffff0000u); } while (0)
; DI void nsa_item(KA a, LAS unsigned char* lds, const int it) {
;     ...
;         if (i + 1 < n) { if (i & 1) NSA_STORE(Kt, VT); else NSA_STORE(Kt1, VT1); if (i + 2 < n) NSA_LOAD(LIST[i + 2]); }
.LBB0_800:
	s_add_i32 s79, s87, 1
	s_cmp_ge_i32 s79, s84
	s_cbranch_scc1 .Lnsa_rsskip0
	s_bitcmp1_b32 s87, 0
	s_cselect_b32 s74, 0, 0x9000
	s_cselect_b32 s75, 0, 0x6c00
	v_add_u32_e32 v144, s74, v142
	v_add_u32_e32 v191, s75, v138
	s_waitcnt vmcnt(0)
	v_perm_b32 v89, v128, v126, s100
	v_perm_b32 v139, v128, v126, s101
	v_perm_b32 v140, v129, v127, s100
	v_perm_b32 v143, v129, v127, s101
	ds_write_b128 v144, v[80:83]
	ds_write2_b32 v191, v89, v139 offset1:68
	ds_write2_b32 v191, v140, v143 offset0:136 offset1:204
	s_add_i32 s79, s87, 2
	s_cmp_ge_i32 s79, s84
	s_cbranch_scc1 .Lnsa_rsskip
	v_readfirstlane_b32 s90, v250
	s_movk_i32 s76, 0x1660
	s_and_b32 s79, s90, 0xff
	s_mul_i32 s79, s79, 0x70000
	s_cmpk_lt_u32 s90, 0x100
	s_cselect_b32 s76, s76, 0x1860
	s_add_u32 s79, s79, s76
	s_add_u32 s76, s98, s79
	s_addc_u32 s77, s99, 0
	global_load_dwordx4 v[80:83], v190, s[76:77]
	global_load_dwordx2 v[126:127], v251, s[76:77]
	global_load_dwordx2 v[128:129], v241, s[76:77]
	v_readlane_b32 s90, v254, 47

; DI f32x16 mma32(bf16x8 a, bf16x8 b, f32x16 c) { return __builtin_amdgcn_mfma_f32_32x32x16_bf16(a, b, c, 0, 0, 0); }
; DI bf16x8 packp(const f32x16& x, const int h8) { v4u p; p.x = pk2(x[h8 + 0], x[h8 + 1]); p.y = pk2(x[h8 + 2], x[h8 + 3]); p.z = pk2(x[h8 + 4], x[h8 + 5]); p.w = pk2(x[h8 + 6], x[h8 + 7]); return __builtin_bit_cast(bf16x8, p); }
; #define NSA_STORE(Kb, Vb) do { *(LAS v4u*)((Kb) + skey * PA + 8 * sch) = kreg; LAS unsigned* d0_ = (LAS unsigned*)((Vb) + (4 * sdg) * PV + vpos(2 * skp)); \
;         d0_[0] = (vr0.x & 0xffffu) | (vr1.x << 16); d0_[PV / 2] = (vr0.x >> 16) | (vr1.x & 0xffff0000u); d0_[PV] = (vr0.y & 0xffffu) | (vr1.y << 16); d0_[3 * PV / 2] = (vr0.y >> 16) | (vr1.y & 0xffff0000u); } while (0)
; DI void nsa_item(KA a, LAS unsigned char* lds, const int it) {
;     ...
;     for (int i = 0; i < n; ++i) {
;         const int desc = LIST[i]; const int ty = desc >> 8, j = desc & 255;
;     ...
;         l_run += ls2[0] + ls2[1];
; #pragma unroll
;         for (int sp = 0; sp < 4; ++sp) { const bf16x8 pf = packp(st[sp >> 1], 8 * (sp & 1));
; #pragma unroll
;             for (int dh = 0; dh < 2; ++dh) ot[dh] = mma32(vfrag(Vc, 32 * dh + r, sp, hf), pf, ot[dh]); }
;         if (i + 1 < n) { if (i & 1) NSA_STORE(Kt, VT); else NSA_STORE(Kt1, VT1); if (i + 2 < n) NSA_LOAD(LIST[i + 2]); }
;         __syncthreads();
;     }
.LBB0_807:
	v_add_u32_e32 v244, 4, v244
	ds_read_b32 v191, v244
	ds_read_b32 v250, v244 offset:8
	ds_read_b128 v[210:213], v230
	ds_read_b128 v[218:221], v230 offset:8704
	ds_read_b128 v[222:225], v230 offset:8736
	ds_read_b128 v[214:217], v230 offset:32
	ds_read_b128 v[226:229], v230 offset:64
	ds_read_b128 v[152:155], v230 offset:8768
	ds_read_b128 v[246:249], v230 offset:96
	ds_read_b128 v[144:147], v231
	ds_read_b128 v[148:151], v231 offset:32
	v_pk_add_f32 v[48:49], v[48:49], v[50:51]
	v_pk_add_f32 v[52:53], v[52:53], v[54:55]
	v_pk_add_f32 v[56:57], v[56:57], v[58:59]
	v_pk_add_f32 v[60:61], v[60:61], v[62:63]
	v_pk_add_f32 v[32:33], v[32:33], v[34:35]
	v_pk_add_f32 v[36:37], v[36:37], v[38:39]
	v_pk_add_f32 v[40:41], v[40:41], v[42:43]
	v_pk_add_f32 v[44:45], v[44:45], v[46:47]
	v_pk_add_f32 v[48:49], v[48:49], v[52:53]
	v_pk_add_f32 v[56:57], v[56:57], v[60:61]
	v_pk_add_f32 v[32:33], v[32:33], v[36:37]
	v_pk_add_f32 v[40:41], v[40:41], v[44:45]
	s_cmp_lg_u32 s84, s76
	v_pk_add_f32 v[48:49], v[48:49], v[56:57]
	v_pk_add_f32 v[32:33], v[32:33], v[40:41]
	s_nop 0
	v_pk_add_f32 v[32:33], v[32:33], v[48:49]
	s_nop 0
	v_add_f32_e32 v32, v32, v33
	v_add_f32_e32 v135, v135, v32
	s_cbranch_scc0 .Lnsa_rot_exit
	s_mov_b32 s87, s76
	s_branch .LBB0_796
